# one static s_setprio 1 for waves 4-7 across the attention KV loop (reset at loop exit)
# speedup vs baseline: 1.0028x; 1.0028x over previous
; DEV int get_tid() { int t = threadIdx.x; asm volatile("" : "+v"(t)); return t; }
; DEV void attn_item(const Params& p, int layer, int h, int qb, float lam, bf16_t* lds) {
;     ...
;   const int tid = get_tid(), lane = tid & 63, wave = tid >> 6;
;   const int lr = lane & 15, lg = lane >> 4;
;   const int grp = wave >> 2, wq = wave & 3;
;   const int t0 = qb * 128;
;   const int lrow = tid >> 4, lc8 = (tid & 15) * 8;
;   const bf16_t* gq = DQ + (size_t)(t0 + wq * 32 + lr) * 1024 + h * 128 + grp * 64 + lg * 8;
;   const bf16x8 a00 = *(const bf16x8*)(gq);
;   const bf16x8 a01 = *(const bf16x8*)(gq + 32);
;   const bf16x8 a10 = *(const bf16x8*)(gq + (size_t)16 * 1024);
;   const bf16x8 a11 = *(const bf16x8*)(gq + (size_t)16 * 1024 + 32);
;   f32x4 o[2][8];
; #pragma unroll
;   for (int i = 0; i < 2; i++)
; #pragma unroll
;     for (int j = 0; j < 8; j++) o[i][j] = (f32x4){0.f, 0.f, 0.f, 0.f};
;   float mrun0 = -1e30f, mrun1 = -1e30f, lrun0 = 0.f, lrun1 = 0.f;
;   u32x4 rk0, rk1, rk2, rk3, rv0, rv1, rv2, rv3;
;   const unsigned ko = (unsigned)(lrow * 1024 + h * 128 + lc8);
;   const unsigned vo = (unsigned)((h * 128 + lrow) * LT + lc8);
;     ...
;   ALOAD(0)
;   const int qrow0 = t0 + wq * 32 + lr;
;   __syncthreads();
;   ASTORE(KV + lrow * PS + lc8)
;   {
;     const int kb1 = qb > 0 ? 1 : 0;
;     ALOAD(kb1)
.LBB0_706:
	v_mov_b32_e32 v224, v181
	s_ashr_i32 s0, s2, 3
	s_sub_i32 s76, 64, s0
	v_lshrrev_b32_e32 v2, 1, v224
	v_and_b32_e32 v226, 0x60, v2
	v_and_b32_e32 v222, 15, v224
	v_lshlrev_b32_e32 v0, 3, v224
	v_lshl_or_b32 v223, s76, 7, v226
	s_lshl_b32 s1, s2, 7
	v_ashrrev_i32_e32 v84, 4, v224
	v_or_b32_e32 v184, v223, v222
	v_mov_b32_e32 v185, v1
	v_readlane_b32 s6, v254, 55
	s_and_b32 s75, s1, 0x380
	v_and_b32_e32 v85, 0x78, v0
	v_lshlrev_b32_e32 v0, 10, v84
	v_ashrrev_i32_e32 v225, 8, v224
	v_lshlrev_b64 v[2:3], 11, v[184:185]
	v_readlane_b32 s7, v254, 56
	v_or3_b32 v186, v0, s75, v85
	v_add_u32_e32 v0, s75, v84
	s_movk_i32 s1, 0x2080
	v_lshl_add_u64 v[2:3], s[6:7], 0, v[2:3]
	s_lshl_b32 s82, s75, 1
	v_lshlrev_b32_e32 v4, 6, v225
	v_mul_lo_u32 v0, v0, s1
	v_lshl_add_u64 v[2:3], v[2:3], 0, s[82:83]
	v_ashrrev_i32_e32 v5, 31, v4
	v_or_b32_e32 v188, v0, v85
	v_mov_b32_e32 v187, v1
	v_add_u32_e32 v0, 0x8000, v186
	v_lshl_add_u64 v[2:3], v[4:5], 1, v[2:3]
	v_lshl_add_u64 v[4:5], v[186:187], 1, s[78:79]
	v_lshl_add_u64 v[6:7], v[0:1], 1, s[78:79]
	v_add_u32_e32 v0, 0x10000, v186
	global_load_dwordx4 v[52:55], v[4:5], off
	global_load_dwordx4 v[56:59], v[6:7], off
	v_lshl_add_u64 v[4:5], v[0:1], 1, s[78:79]
	v_add_u32_e32 v0, 0x18000, v186
	v_lshl_add_u64 v[6:7], v[0:1], 1, s[78:79]
	v_mov_b32_e32 v189, v1
	v_add_u32_e32 v0, 0x41000, v188
	global_load_dwordx4 v[60:63], v[4:5], off
	global_load_dwordx4 v[64:67], v[6:7], off
	v_lshl_add_u64 v[4:5], v[188:189], 1, s[70:71]
	v_lshl_add_u64 v[6:7], v[0:1], 1, s[70:71]
	v_add_u32_e32 v0, 0x82000, v188
	v_and_b32_e32 v182, 48, v224
	v_mov_b32_e32 v183, v1
	global_load_dwordx4 v[68:71], v[4:5], off
	global_load_dwordx4 v[72:75], v[6:7], off
	v_lshl_add_u64 v[4:5], v[0:1], 1, s[70:71]
	v_add_u32_e32 v0, 0xc3000, v188
	global_load_dwordx4 v[76:79], v[4:5], off
	v_lshl_add_u64 v[4:5], v[0:1], 1, s[70:71]
	v_lshl_add_u64 v[2:3], v[2:3], 0, v[182:183]
	s_mov_b32 s1, 0x8000
	s_cmp_eq_u32 s0, 64
	global_load_dwordx4 v[80:83], v[4:5], off
	s_nop 0
	global_load_dwordx4 v[4:7], v[2:3], off
	global_load_dwordx4 v[8:11], v[2:3], off offset:64
	v_add_co_u32_e32 v2, vcc, s1, v2
	s_cselect_b32 s1, 0, 0x20000
	v_add_u32_e32 v0, s1, v186
	v_addc_co_u32_e32 v3, vcc, 0, v3, vcc
	v_add_u32_e32 v20, 0x8000, v0
	v_mov_b32_e32 v21, v1
	global_load_dwordx4 v[12:15], v[2:3], off
	global_load_dwordx4 v[16:19], v[2:3], off offset:64
	v_lshl_add_u64 v[2:3], v[0:1], 1, s[78:79]
	v_lshl_add_u64 v[24:25], v[20:21], 1, s[78:79]
	s_barrier
; DEV void attn_item(const Params& p, int layer, int h, int qb, float lam, bf16_t* lds) {
;     ...
;   f32x4 o[2][8];
; #pragma unroll
;   for (int i = 0; i < 2; i++)
; #pragma unroll
;     for (int j = 0; j < 8; j++) o[i][j] = (f32x4){0.f, 0.f, 0.f, 0.f};
;   float mrun0 = -1e30f, mrun1 = -1e30f, lrun0 = 0.f, lrun1 = 0.f;
;   u32x4 rk0, rk1, rk2, rk3, rv0, rv1, rv2, rv3;
;   const unsigned ko = (unsigned)(lrow * 1024 + h * 128 + lc8);
;   const unsigned vo = (unsigned)((h * 128 + lrow) * LT + lc8);
;     ...
;   ALOAD(0)
;   const int qrow0 = t0 + wq * 32 + lr;
;   __syncthreads();
;   ASTORE(KV + lrow * PS + lc8)
;   {
;     const int kb1 = qb > 0 ? 1 : 0;
;     ALOAD(kb1)
;   }
;   __syncthreads();
	global_load_dwordx4 v[20:23], v[2:3], off
	s_nop 0
	global_load_dwordx4 v[24:27], v[24:25], off
	v_add_u32_e32 v2, 0x10000, v0
	v_add_u32_e32 v0, 0x18000, v0
	s_cselect_b32 s1, 0, 0x80
	v_mov_b32_e32 v3, v1
	v_lshl_add_u64 v[32:33], v[0:1], 1, s[78:79]
	v_add_u32_e32 v0, s1, v188
	v_lshl_add_u64 v[2:3], v[2:3], 1, s[78:79]
	v_add_u32_e32 v36, 0x41000, v0
	v_mov_b32_e32 v37, v1
	global_load_dwordx4 v[28:31], v[2:3], off
	s_nop 0
	global_load_dwordx4 v[32:35], v[32:33], off
	v_lshl_add_u64 v[2:3], v[0:1], 1, s[70:71]
	v_lshl_add_u64 v[40:41], v[36:37], 1, s[70:71]
	global_load_dwordx4 v[36:39], v[2:3], off
	s_nop 0
	global_load_dwordx4 v[40:43], v[40:41], off
	v_add_u32_e32 v2, 0x82000, v0
	v_mov_b32_e32 v3, v1
	v_add_u32_e32 v0, 0xc3000, v0
	v_lshl_add_u64 v[2:3], v[2:3], 1, s[70:71]
	v_lshl_add_u64 v[48:49], v[0:1], 1, s[70:71]
	global_load_dwordx4 v[44:47], v[2:3], off
	s_nop 0
	global_load_dwordx4 v[48:51], v[48:49], off
	s_movk_i32 s1, 0x110
	v_mul_lo_u32 v84, v84, s1
	v_lshlrev_b32_e32 v85, 1, v85
	v_add3_u32 v230, 0, v84, v85
	v_and_b32_e32 v0, 15, v181
	v_bfe_u32 v2, v181, 4, 4
	v_not_b32_e32 v3, v2
	v_and_b32_e32 v3, 1, v3
	v_lshlrev_b32_e32 v3, 1, v3
	v_add_u32_e32 v2, 4, v2
	v_bfe_u32 v2, v2, 3, 1
	v_or_b32_e32 v3, v3, v2
	v_xor_b32_e32 v3, v3, v0
	v_sub_u32_e32 v3, v3, v0
	v_lshl_add_u32 v230, v3, 4, v230
	s_waitcnt vmcnt(19)
	ds_write_b128 v230, v[52:55]
	s_waitcnt vmcnt(18)
	ds_write_b128 v230, v[56:59] offset:8704
	s_waitcnt vmcnt(17)
	ds_write_b128 v230, v[60:63] offset:17408
	s_waitcnt vmcnt(16)
	ds_write_b128 v230, v[64:67] offset:26112
	s_mov_b32 s98, 0x11000
	v_and_b32_e32 v0, 15, v181
	v_bfe_u32 v2, v181, 4, 4
	v_not_b32_e32 v54, v2
	v_and_b32_e32 v54, 1, v54
	v_lshlrev_b32_e32 v54, 1, v54
	v_add_u32_e32 v55, 4, v2
	v_bfe_u32 v55, v55, 3, 1
	v_or_b32_e32 v54, v54, v55
	v_xor_b32_e32 v3, v0, v54
	v_lshlrev_b32_e32 v3, 4, v3
	v_sub_u32_e32 v3, v230, v3
	v_add_u32_e32 v3, s98, v3
	v_lshrrev_b32_e32 v55, 2, v0
	v_lshl_add_u32 v3, v55, 6, v3
	v_bfe_u32 v55, v0, 1, 1
	v_lshl_add_u32 v3, v55, 3, v3
	v_and_b32_e32 v55, 1, v0
	v_lshlrev_b32_e32 v55, 1, v55
	v_xor_b32_e32 v55, v55, v54
	v_xor_b32_e32 v54, 1, v55
	v_lshl_add_u32 v52, v55, 4, v3
	v_lshl_add_u32 v53, v54, 4, v3
	v_mov_b32_e32 v204, v52
	v_mov_b32_e32 v205, v53
	v_bfe_u32 v2, v224, 4, 2
	v_not_b32_e32 v3, v222
	v_and_b32_e32 v3, 1, v3
	v_lshlrev_b32_e32 v3, 1, v3
	v_add_u32_e32 v55, 4, v222
	v_bfe_u32 v55, v55, 3, 1
	v_or_b32_e32 v3, v3, v55
	v_xor_b32_e32 v3, v3, v2
	v_lshlrev_b32_e32 v3, 4, v3
	v_readlane_b32 s1, v255, 8
	s_waitcnt vmcnt(15)
	ds_write_b64 v52, v[68:69]
	ds_write_b64 v53, v[70:71]
	s_waitcnt vmcnt(14)
	ds_write_b64 v52, v[72:73] offset:8704
	ds_write_b64 v53, v[74:75] offset:8704
	s_waitcnt vmcnt(13)
	ds_write_b64 v52, v[76:77] offset:17408
	ds_write_b64 v53, v[78:79] offset:17408
	v_and_b32_e32 v0, 63, v224
	v_lshlrev_b32_e32 v54, 7, v225
	v_lshlrev_b32_e32 v183, 2, v2
	s_waitcnt vmcnt(12)
	ds_write_b64 v52, v[80:81] offset:26112
	ds_write_b64 v53, v[82:83] offset:26112
	v_mul_u32_u24_e32 v52, 0x88, v222
	v_lshlrev_b32_e32 v52, 1, v52
	v_add_u32_e32 v53, 0, v52
	v_add3_u32 v232, s1, v52, v3
	v_add3_u32 v231, v53, v54, v3
	v_mov_b32_e32 v2, v1
	v_mov_b32_e32 v3, v1
	v_lshlrev_b32_e32 v185, 2, v0
	v_mov_b32_e32 v0, v1
	v_mov_b32_e32 v192, 0xf149f2ca
	v_mov_b32_e32 v190, 0
	v_mov_b64_e32 v[58:59], v[2:3]
	v_mov_b64_e32 v[62:63], v[2:3]
	v_mov_b64_e32 v[66:67], v[2:3]
	v_mov_b64_e32 v[70:71], v[2:3]
	v_mov_b64_e32 v[74:75], v[2:3]
	v_mov_b64_e32 v[78:79], v[2:3]
	v_mov_b64_e32 v[82:83], v[2:3]
	v_mov_b64_e32 v[86:87], v[2:3]
	v_mov_b64_e32 v[106:107], v[2:3]
	v_mov_b64_e32 v[90:91], v[2:3]
	v_mov_b64_e32 v[110:111], v[2:3]
	v_mov_b64_e32 v[94:95], v[2:3]
	v_mov_b64_e32 v[114:115], v[2:3]
	v_mov_b64_e32 v[98:99], v[2:3]
	v_mov_b64_e32 v[102:103], v[2:3]
	v_mov_b64_e32 v[54:55], v[2:3]
	v_mov_b32_e32 v217, 0x3e38aa3b
	v_mov_b32_e32 v180, 0x42000000
	s_mov_b32 s77, 0
	v_xor_b32_e32 v229, 64, v185
	v_xor_b32_e32 v228, 0x80, v185
	v_or_b32_e32 v233, 16, v184
	v_or_b32_e32 v227, 4, v182
	v_or_b32_e32 v189, 8, v182
	v_or_b32_e32 v187, 12, v182
	s_sub_i32 s82, 0x41, s0
	v_mov_b32_e32 v234, v183
	v_mov_b64_e32 v[56:57], v[0:1]
	v_mov_b64_e32 v[60:61], v[0:1]
	v_mov_b64_e32 v[64:65], v[0:1]
	v_mov_b64_e32 v[68:69], v[0:1]
	v_mov_b64_e32 v[72:73], v[0:1]
	v_mov_b64_e32 v[76:77], v[0:1]
	v_mov_b64_e32 v[80:81], v[0:1]
	v_mov_b64_e32 v[84:85], v[0:1]
	v_mov_b64_e32 v[104:105], v[0:1]
	v_mov_b64_e32 v[88:89], v[0:1]
	v_mov_b64_e32 v[108:109], v[0:1]
	v_mov_b64_e32 v[92:93], v[0:1]
	v_mov_b64_e32 v[112:113], v[0:1]
	v_mov_b64_e32 v[96:97], v[0:1]
	v_mov_b64_e32 v[100:101], v[0:1]
	v_mov_b64_e32 v[52:53], v[0:1]
	v_mov_b32_e32 v191, v190
	v_mov_b32_e32 v193, v192
	v_readfirstlane_b32 s99, v181
	s_lshr_b32 s99, s99, 8
	s_cmp_eq_u32 s99, 0
	s_cbranch_scc1 .Lprio_skip
	s_setprio 1
.Lprio_skip:
	s_waitcnt lgkmcnt(0)
	s_barrier
	s_branch .LBB0_708

; DEV float shfl_xor_l(float v, int m, int lane) { return __int_as_float(__builtin_amdgcn_ds_bpermute((lane ^ m) << 2, __float_as_int(v))); }
; DEV float shfl_l(float v, int srclane) { return __int_as_float(__builtin_amdgcn_ds_bpermute(srclane << 2, __float_as_int(v))); }
; DEV void attn_item(const Params& p, int layer, int h, int qb, float lam, bf16_t* lds) {
;     ...
; #pragma unroll
;   for (int i = 0; i < 2; i++) {
;     float l = i == 0 ? lrun0 : lrun1;
;     l += shfl_xor_l(l, 16, lane);
;     l += shfl_xor_l(l, 32, lane);
;     const float inv = l > 0.f ? 1.f / l : 0.f;
; #pragma unroll
;     for (int r = 0; r < 4; r++) {
;       const float ir = shfl_l(inv, lg * 4 + r);
; #pragma unroll
;       for (int je = 0; je < 8; je++) o[i][je][r] *= ir;
;     }
;   }
;   __syncthreads();
;   if (grp == 1) {
; #pragma unroll
;     for (int i = 0; i < 2; i++)
; #pragma unroll
;       for (int je = 0; je < 8; je++)
; #pragma unroll
;         for (int r = 0; r < 4; r++) X[(wq * 32 + i * 16 + lg * 4 + r) * XS + je * 16 + lr] = o[i][je][r];
;   }
.LBB0_712:
	s_setprio 0
	ds_bpermute_b32 v3, v229, v191
	ds_bpermute_b32 v2, v229, v190
	v_mov_b32_e32 v4, v112
	v_mov_b32_e32 v5, v92
	v_mov_b32_e32 v9, v84
	v_mov_b32_e32 v92, v113
	s_waitcnt lgkmcnt(0)
	v_pk_add_f32 v[2:3], v[190:191], v[2:3]
	ds_bpermute_b32 v11, v228, v3
	ds_bpermute_b32 v10, v228, v2
	v_mov_b32_e32 v84, v105
	v_mov_b32_e32 v12, v114
	v_mov_b32_e32 v13, v94
	v_mov_b32_e32 v14, v106
	s_waitcnt lgkmcnt(0)
	v_pk_add_f32 v[2:3], v[2:3], v[10:11]
	v_mov_b32_e32 v10, v110
	v_div_scale_f32 v0, s[0:1], v3, v3, 1.0
	v_rcp_f32_e32 v15, v0
	v_mov_b32_e32 v11, v90
	v_mov_b32_e32 v7, v88
	v_mov_b32_e32 v88, v109
	v_fma_f32 v16, -v0, v15, 1.0
	v_fmac_f32_e32 v15, v16, v15
	v_div_scale_f32 v16, vcc, 1.0, v3, 1.0
	v_mul_f32_e32 v17, v16, v15
	v_fma_f32 v18, -v0, v17, v16
	v_fmac_f32_e32 v17, v18, v15
	v_fma_f32 v0, -v0, v17, v16
	v_div_fmas_f32 v0, v0, v15, v17
	v_div_fixup_f32 v0, v0, v3, 1.0
	v_cmp_lt_f32_e32 vcc, 0, v3
	v_mov_b32_e32 v15, v86
	v_div_scale_f32 v3, s[0:1], v2, v2, 1.0
	v_cndmask_b32_e32 v0, 0, v0, vcc
	ds_bpermute_b32 v16, v182, v0
	ds_bpermute_b32 v17, v227, v0
	v_mov_b32_e32 v86, v107
	v_mov_b32_e32 v94, v115
	v_mov_b32_e32 v90, v111
	v_mov_b32_e32 v6, v108
	s_waitcnt vmcnt(2) lgkmcnt(0)
	v_pk_mul_f32 v[40:41], v[4:5], v[16:17] op_sel_hi:[1,0]
	ds_bpermute_b32 v4, v189, v0
	ds_bpermute_b32 v5, v187, v0
	v_mov_b32_e32 v0, v17
	s_waitcnt vmcnt(1)
	v_pk_mul_f32 v[46:47], v[100:101], v[16:17]
	v_pk_mul_f32 v[42:43], v[92:93], v[0:1] op_sel_hi:[1,0]
	s_waitcnt vmcnt(0)
	v_pk_mul_f32 v[50:51], v[84:85], v[0:1] op_sel_hi:[1,0]
	s_waitcnt lgkmcnt(0)
	v_pk_mul_f32 v[106:107], v[12:13], v[4:5] op_sel_hi:[1,0]
	v_pk_mul_f32 v[84:85], v[10:11], v[4:5] op_sel_hi:[1,0]
	v_pk_mul_f32 v[36:37], v[14:15], v[4:5] op_sel_hi:[1,0]
	v_pk_mul_f32 v[100:101], v[102:103], v[4:5]
	v_pk_mul_f32 v[92:93], v[98:99], v[4:5]
	v_rcp_f32_e32 v4, v3
	v_pk_mul_f32 v[44:45], v[96:97], v[16:17]
	v_pk_mul_f32 v[96:97], v[88:89], v[0:1] op_sel_hi:[1,0]
	v_mov_b32_e32 v0, v5
	v_pk_mul_f32 v[94:95], v[94:95], v[0:1] op_sel_hi:[1,0]
	v_pk_mul_f32 v[88:89], v[90:91], v[0:1] op_sel_hi:[1,0]
	v_pk_mul_f32 v[38:39], v[86:87], v[0:1] op_sel_hi:[1,0]
	v_fma_f32 v0, -v3, v4, 1.0
	v_fmac_f32_e32 v4, v0, v4
	v_div_scale_f32 v0, vcc, 1.0, v2, 1.0
	v_mul_f32_e32 v5, v0, v4
	v_mov_b32_e32 v8, v104
	v_pk_mul_f32 v[104:105], v[6:7], v[16:17] op_sel_hi:[1,0]
	v_fma_f32 v6, -v3, v5, v0
	v_fmac_f32_e32 v5, v6, v4
	v_fma_f32 v0, -v3, v5, v0
	v_div_fmas_f32 v0, v0, v4, v5
	v_div_fixup_f32 v0, v0, v2, 1.0
	v_cmp_lt_f32_e32 vcc, 0, v2
	v_pk_mul_f32 v[48:49], v[8:9], v[16:17] op_sel_hi:[1,0]
	v_mov_b32_e32 v4, v72
	v_cndmask_b32_e32 v10, 0, v0, vcc
	ds_bpermute_b32 v2, v182, v10
	ds_bpermute_b32 v3, v227, v10
	v_mov_b32_e32 v5, v68
	v_mov_b32_e32 v6, v64
	v_mov_b32_e32 v7, v60
	v_mov_b32_e32 v8, v56
	v_mov_b32_e32 v9, v52
	s_waitcnt lgkmcnt(0)
	v_pk_mul_f32 v[26:27], v[4:5], v[2:3] op_sel_hi:[1,0]
	v_pk_mul_f32 v[20:21], v[6:7], v[2:3] op_sel_hi:[1,0]
	v_pk_mul_f32 v[12:13], v[8:9], v[2:3] op_sel_hi:[1,0]
	v_pk_mul_f32 v[24:25], v[80:81], v[2:3]
	v_pk_mul_f32 v[22:23], v[76:77], v[2:3]
	v_mov_b32_e32 v0, v3
	ds_bpermute_b32 v3, v187, v10
	ds_bpermute_b32 v2, v189, v10
	v_mov_b32_e32 v68, v73
	v_mov_b32_e32 v60, v65
	v_mov_b32_e32 v52, v57
	v_pk_mul_f32 v[28:29], v[68:69], v[0:1] op_sel_hi:[1,0]
	v_pk_mul_f32 v[18:19], v[60:61], v[0:1] op_sel_hi:[1,0]
	v_pk_mul_f32 v[16:17], v[52:53], v[0:1] op_sel_hi:[1,0]
	v_mov_b32_e32 v4, v74
	v_mov_b32_e32 v5, v70
	v_mov_b32_e32 v7, v62
	v_mov_b32_e32 v8, v58
	v_mov_b32_e32 v9, v54
	v_mov_b32_e32 v70, v75
	s_waitcnt lgkmcnt(1)
	v_mov_b32_e32 v0, v3
	v_mov_b32_e32 v62, v67
	v_mov_b32_e32 v54, v59
	v_mov_b32_e32 v6, v66
	s_waitcnt lgkmcnt(0)
	v_pk_mul_f32 v[32:33], v[4:5], v[2:3] op_sel_hi:[1,0]
	v_pk_mul_f32 v[4:5], v[8:9], v[2:3] op_sel_hi:[1,0]
	v_pk_mul_f32 v[34:35], v[70:71], v[0:1] op_sel_hi:[1,0]
	v_pk_mul_f32 v[10:11], v[62:63], v[0:1] op_sel_hi:[1,0]
	v_pk_mul_f32 v[8:9], v[54:55], v[0:1] op_sel_hi:[1,0]
	v_or_b32_e32 v0, v183, v226
	v_pk_mul_f32 v[6:7], v[6:7], v[2:3] op_sel_hi:[1,0]
	v_pk_mul_f32 v[30:31], v[82:83], v[2:3]
	v_pk_mul_f32 v[14:15], v[78:79], v[2:3]
	v_cmp_eq_u32_e32 vcc, 1, v225
	v_lshlrev_b32_e32 v3, 2, v222
	v_mul_u32_u24_e32 v52, 0x210, v0
	s_barrier
	s_and_saveexec_b64 s[0:1], vcc
	s_cbranch_execz .LBB0_714
	v_add3_u32 v0, 0, v3, v52
	v_add_u32_e32 v2, 0x400, v0
	ds_write2_b32 v0, v46, v44 offset1:16
	ds_write2_b32 v0, v47, v45 offset0:132 offset1:148
	ds_write2_b32 v2, v100, v92 offset0:8 offset1:24
	ds_write2_b32 v2, v101, v93 offset0:140 offset1:156
	ds_write2_b32 v0, v40, v41 offset0:32 offset1:48
	ds_write2_b32 v0, v42, v43 offset0:164 offset1:180
	ds_write2_b32 v2, v106, v107 offset0:40 offset1:56
	ds_write2_b32 v2, v94, v95 offset0:172 offset1:188
	ds_write2_b32 v0, v104, v105 offset0:64 offset1:80
	ds_write2_b32 v0, v96, v97 offset0:196 offset1:212
	ds_write2_b32 v2, v84, v85 offset0:72 offset1:88
	ds_write2_b32 v2, v88, v89 offset0:204 offset1:220
	ds_write2_b32 v0, v48, v49 offset0:96 offset1:112
	ds_write2_b32 v0, v50, v51 offset0:228 offset1:244
	ds_write2_b32 v2, v36, v37 offset0:104 offset1:120
	ds_write2_b32 v2, v38, v39 offset0:236 offset1:252
	v_add_u32_e32 v2, 0x2000, v0
	v_add_u32_e32 v53, 0x2400, v0
	v_add_u32_e32 v0, 0x2800, v0
	ds_write2_b32 v2, v24, v22 offset0:64 offset1:80
	ds_write2_b32 v2, v25, v23 offset0:196 offset1:212
	ds_write2_b32 v53, v30, v14 offset0:72 offset1:88
	ds_write2_b32 v53, v31, v15 offset0:204 offset1:220
	ds_write2_b32 v2, v26, v27 offset0:96 offset1:112
	ds_write2_b32 v2, v28, v29 offset0:228 offset1:244
	ds_write2_b32 v53, v32, v33 offset0:104 offset1:120
	ds_write2_b32 v53, v34, v35 offset0:236 offset1:252
	ds_write2_b32 v2, v20, v21 offset0:128 offset1:144
	ds_write2_b32 v53, v18, v19 offset0:4 offset1:20
	ds_write2_b32 v53, v6, v7 offset0:136 offset1:152
	ds_write2_b32 v0, v10, v11 offset0:12 offset1:28
	ds_write2_b32 v2, v12, v13 offset0:160 offset1:176
	ds_write2_b32 v53, v16, v17 offset0:36 offset1:52
	ds_write2_b32 v53, v4, v5 offset0:168 offset1:184
	ds_write2_b32 v0, v8, v9 offset0:44 offset1:60
